# v86 + counted lgkmcnt waits in the last P.V of each attention unit; one wait state less before the first QK^T MFMA of the uniform path
# baseline (speedup 1.0000x reference)
; #define SBAR() __builtin_amdgcn_sched_barrier(0)
; template <int D0> __device__ __forceinline__ void pv_one(f32x16& od, int vb, bf16x8 pa0, bf16x8 pa1, bf16x8 pa2, bf16x8 pa3) {
;   const s16x4 l0 = tr_read<v_rd_off(D0, 0, 0)>(vb), h0 = tr_read<v_rd_off(D0, 0, 1)>(vb), l1 = tr_read<v_rd_off(D0, 1, 0)>(vb), h1 = tr_read<v_rd_off(D0, 1, 1)>(vb);
;   const s16x4 l2 = tr_read<v_rd_off(D0, 2, 0)>(vb), h2 = tr_read<v_rd_off(D0, 2, 1)>(vb), l3 = tr_read<v_rd_off(D0, 3, 0)>(vb), h3 = tr_read<v_rd_off(D0, 3, 1)>(vb);
;   asm volatile("s_waitcnt lgkmcnt(0)" ::: "memory"); SBAR();
;     ...
;   od = __builtin_amdgcn_mfma_f32_32x32x16_bf16(pa0, PK(l0, h0), od, 0, 0, 0);
;   od = __builtin_amdgcn_mfma_f32_32x32x16_bf16(pa1, PK(l1, h1), od, 0, 0, 0);
;   od = __builtin_amdgcn_mfma_f32_32x32x16_bf16(pa2, PK(l2, h2), od, 0, 0, 0);
;   od = __builtin_amdgcn_mfma_f32_32x32x16_bf16(pa3, PK(l3, h3), od, 0, 0, 0);
;     ...
; }
; __device__ __forceinline__ void pv_d0(f32x16* o, int vb, bf16x8 pa0, bf16x8 pa1, bf16x8 pa2, bf16x8 pa3) {
; __device__ __forceinline__ void qkt_c(f32x16& p0, f32x16& p1, const char* Ks, const bf16x8* qr, const f32x16& negm, int r32, int hi) {
; #pragma unroll
;   for (int d0 = 0; d0 < 4; ++d0) { const int cb = (d0 * 16 + hi * 8) * 2;
;     bf16x8 b0 = *reinterpret_cast<const bf16x8*>(Ks + KSWZ(r32, cb));
;     bf16x8 b1 = *reinterpret_cast<const bf16x8*>(Ks + KSWZ(32 + r32, cb));
;     if (d0 == 0) { p0 = __builtin_amdgcn_mfma_f32_32x32x16_bf16(b0, qr[0], negm, 0, 0, 0); p1 = __builtin_amdgcn_mfma_f32_32x32x16_bf16(b1, qr[0], negm, 0, 0, 0); }
;     else { p0 = __builtin_amdgcn_mfma_f32_32x32x16_bf16(b0, qr[d0], p0, 0, 0, 0); p1 = __builtin_amdgcn_mfma_f32_32x32x16_bf16(b1, qr[d0], p1, 0, 0, 0); } }
; }
; template <int R> __device__ __forceinline__ void bias_r(f32x16& p0, f32x16& p1, float dq, float nslope) {
;   constexpr int C0 = (R & 3) + 8 * (R >> 2);
;   float x0, x1, a0 = p0[R], a1 = p1[R];
;   asm("v_sub_f32_e32 %0, %1, %2" : "=v"(x0) : "n"(__builtin_bit_cast(int, (float)C0)), "v"(dq));
;   asm("v_sub_f32_e32 %0, %1, %2" : "=v"(x1) : "n"(__builtin_bit_cast(int, (float)(C0 + 32))), "v"(dq));
;   asm("v_fma_f32 %0, %1, |%2|, %0" : "+v"(a0) : "v"(nslope), "v"(x0));
;   asm("v_fma_f32 %0, %1, |%2|, %0" : "+v"(a1) : "v"(nslope), "v"(x1));
;   p0[R] = a0; p1[R] = a1;
;   if constexpr (R < 15) bias_r<R + 1>(p0, p1, dq, nslope);
; }
.LBB0_364:
	ds_read_b128 v[114:117], v195 offset:32768
	ds_read_b128 v[212:215], v196 offset:32768
	ds_read_b128 v[216:219], v197 offset:32768
	s_and_b64 vcc, exec, s[14:15]
	s_add_i32 s72, s22, s46
	s_cmp_lt_i32 s46, s23
	s_cselect_b32 s14, s72, s39
	s_lshl_b32 s74, s14, 1
	s_sub_i32 s74, s74, s99
	s_add_i32 s75, s74, 1
	s_lshl_b32 s14, s14, 6
	v_cvt_f32_i32_e32 v0, s14
	v_sub_f32_e32 v0, v192, v0
	s_cmp_lt_u32 s75, 2
	s_cbranch_scc1 .Lbc_mix_0
	s_and_b32 s75, s74, 0x80000000
	v_xor_b32_e32 v14, s75, v81
	v_fma_f32 v15, -v14, v0, v82
	v_fmamk_f32 v240, v14, 0x00000000, v15
	v_fmamk_f32 v241, v14, 0x3f800000, v15
	v_fmamk_f32 v242, v14, 0x40000000, v15
	v_fmamk_f32 v243, v14, 0x40400000, v15
	v_fmamk_f32 v244, v14, 0x41000000, v15
	v_fmamk_f32 v245, v14, 0x41100000, v15
	v_fmamk_f32 v246, v14, 0x41200000, v15
	v_fmamk_f32 v247, v14, 0x41300000, v15
	v_fmamk_f32 v248, v14, 0x41800000, v15
	v_fmamk_f32 v249, v14, 0x41880000, v15
	v_fmamk_f32 v250, v14, 0x41900000, v15
	v_fmamk_f32 v251, v14, 0x41980000, v15
	v_fmamk_f32 v252, v14, 0x41c00000, v15
	v_fmamk_f32 v253, v14, 0x41c80000, v15
	v_fmamk_f32 v254, v14, 0x41d00000, v15
	v_fmamk_f32 v255, v14, 0x41d80000, v15
	s_nop 0
	s_waitcnt lgkmcnt(2)
	v_mfma_f32_32x32x16_bf16 v[98:113], v[114:117], v[130:133], v[240:255]
	ds_read_b128 v[220:223], v198 offset:32768
	s_waitcnt lgkmcnt(2)
	v_mfma_f32_32x32x16_bf16 v[98:113], v[212:215], v[134:137], v[98:113]
	ds_read_b128 v[212:215], v195 offset:40960
	s_waitcnt lgkmcnt(2)
	v_mfma_f32_32x32x16_bf16 v[98:113], v[216:219], v[138:141], v[98:113]
	ds_read_b128 v[216:219], v196 offset:40960
	v_fmamk_f32 v240, v14, 0x42000000, v15
	v_fmamk_f32 v241, v14, 0x42040000, v15
	v_fmamk_f32 v242, v14, 0x42080000, v15
	v_fmamk_f32 v243, v14, 0x420c0000, v15
	v_fmamk_f32 v244, v14, 0x42200000, v15
	v_fmamk_f32 v245, v14, 0x42240000, v15
	v_fmamk_f32 v246, v14, 0x42280000, v15
	v_fmamk_f32 v247, v14, 0x422c0000, v15
	s_waitcnt lgkmcnt(2)
	v_mfma_f32_32x32x16_bf16 v[98:113], v[220:223], v[142:145], v[98:113]
	v_fmamk_f32 v248, v14, 0x42400000, v15
	v_fmamk_f32 v249, v14, 0x42440000, v15
	v_fmamk_f32 v250, v14, 0x42480000, v15
	v_fmamk_f32 v251, v14, 0x424c0000, v15
	v_fmamk_f32 v252, v14, 0x42600000, v15
	v_fmamk_f32 v253, v14, 0x42640000, v15
	v_fmamk_f32 v254, v14, 0x42680000, v15
	v_fmamk_f32 v255, v14, 0x426c0000, v15
	ds_read_b128 v[220:223], v197 offset:40960
	s_waitcnt lgkmcnt(2)
	v_mfma_f32_32x32x16_bf16 v[114:129], v[212:215], v[130:133], v[240:255]
	ds_read_b128 v[212:215], v198 offset:40960
	s_waitcnt lgkmcnt(2)
	v_mfma_f32_32x32x16_bf16 v[114:129], v[216:219], v[134:137], v[114:129]
	s_cbranch_vccnz .Lbc_tail_u_0
	ds_read_b64_tr_b16 v[204:205], v194 offset:0
	ds_read_b64_tr_b16 v[206:207], v194 offset:0x800
	ds_read_b64_tr_b16 v[208:209], v194 offset:0x1000
	ds_read_b64_tr_b16 v[210:211], v194 offset:0x1800
	s_waitcnt lgkmcnt(5)
	v_mfma_f32_32x32x16_bf16 v[114:129], v[220:223], v[138:141], v[114:129]
	s_waitcnt lgkmcnt(4)
	v_mfma_f32_32x32x16_bf16 v[114:129], v[212:215], v[142:145], v[114:129]
	ds_read_b64_tr_b16 v[212:213], v194 offset:0x2000
	ds_read_b64_tr_b16 v[214:215], v194 offset:0x2800
	ds_read_b64_tr_b16 v[216:217], v194 offset:0x3000
	ds_read_b64_tr_b16 v[218:219], v194 offset:0x3800
	s_waitcnt lgkmcnt(6)
	v_mfma_f32_32x32x16_bf16 v[64:79], v[2:5], v[204:207], v[64:79]
	ds_read_b64_tr_b16 v[204:205], v194 offset:0x200
	ds_read_b64_tr_b16 v[206:207], v194 offset:0xa00
	s_waitcnt lgkmcnt(6)
	v_mfma_f32_32x32x16_bf16 v[64:79], v[6:9], v[208:211], v[64:79]
	ds_read_b64_tr_b16 v[208:209], v194 offset:0x1200
	ds_read_b64_tr_b16 v[210:211], v194 offset:0x1a00
	s_waitcnt lgkmcnt(6)
	v_mfma_f32_32x32x16_bf16 v[64:79], v[10:13], v[212:215], v[64:79]
	ds_read_b64_tr_b16 v[212:213], v194 offset:0x2200
	ds_read_b64_tr_b16 v[214:215], v194 offset:0x2a00
	ds_read_b64_tr_b16 v[220:221], v194 offset:0x3200
	ds_read_b64_tr_b16 v[222:223], v194 offset:0x3a00
	s_waitcnt lgkmcnt(8)
	v_mfma_f32_32x32x16_bf16 v[64:79], v[162:165], v[216:219], v[64:79]
	s_waitcnt lgkmcnt(6)
	v_mfma_f32_32x32x16_bf16 v[48:63], v[2:5], v[204:207], v[48:63]
	ds_read_b64_tr_b16 v[204:205], v194 offset:0x400
	ds_read_b64_tr_b16 v[206:207], v194 offset:0xc00
	s_waitcnt lgkmcnt(6)
	v_mfma_f32_32x32x16_bf16 v[48:63], v[6:9], v[208:211], v[48:63]
	ds_read_b64_tr_b16 v[208:209], v194 offset:0x1400
	ds_read_b64_tr_b16 v[210:211], v194 offset:0x1c00
	s_waitcnt lgkmcnt(6)
	v_mfma_f32_32x32x16_bf16 v[48:63], v[10:13], v[212:215], v[48:63]
	ds_read_b64_tr_b16 v[212:213], v194 offset:0x2400
	ds_read_b64_tr_b16 v[214:215], v194 offset:0x2c00
	ds_read_b64_tr_b16 v[216:217], v194 offset:0x3400
	ds_read_b64_tr_b16 v[218:219], v194 offset:0x3c00
	s_waitcnt lgkmcnt(8)
	v_mfma_f32_32x32x16_bf16 v[48:63], v[162:165], v[220:223], v[48:63]
	s_waitcnt lgkmcnt(6)
	v_mfma_f32_32x32x16_bf16 v[32:47], v[2:5], v[204:207], v[32:47]
	ds_read_b64_tr_b16 v[204:205], v194 offset:0x600
	ds_read_b64_tr_b16 v[206:207], v194 offset:0xe00
	s_waitcnt lgkmcnt(6)
	v_mfma_f32_32x32x16_bf16 v[32:47], v[6:9], v[208:211], v[32:47]
	ds_read_b64_tr_b16 v[208:209], v194 offset:0x1600
	ds_read_b64_tr_b16 v[210:211], v194 offset:0x1e00
	s_waitcnt lgkmcnt(6)
	v_mfma_f32_32x32x16_bf16 v[32:47], v[10:13], v[212:215], v[32:47]
	ds_read_b64_tr_b16 v[212:213], v194 offset:0x2600
	ds_read_b64_tr_b16 v[214:215], v194 offset:0x2e00
	ds_read_b64_tr_b16 v[220:221], v194 offset:0x3600
	ds_read_b64_tr_b16 v[222:223], v194 offset:0x3e00
	s_waitcnt lgkmcnt(8)
	v_mfma_f32_32x32x16_bf16 v[32:47], v[162:165], v[216:219], v[32:47]
	s_waitcnt lgkmcnt(6)
	v_mfma_f32_32x32x16_bf16 v[16:31], v[2:5], v[204:207], v[16:31]
	s_waitcnt lgkmcnt(4)
	v_mfma_f32_32x32x16_bf16 v[16:31], v[6:9], v[208:211], v[16:31]
	s_waitcnt lgkmcnt(2)
	v_mfma_f32_32x32x16_bf16 v[16:31], v[10:13], v[212:215], v[16:31]
	s_waitcnt lgkmcnt(0)
	v_mfma_f32_32x32x16_bf16 v[16:31], v[162:165], v[220:223], v[16:31]
	s_barrier
	s_branch .Lafter_bias_0

; #define SBAR() __builtin_amdgcn_sched_barrier(0)
; template <int D0> __device__ __forceinline__ void pv_one(f32x16& od, int vb, bf16x8 pa0, bf16x8 pa1, bf16x8 pa2, bf16x8 pa3) {
;   const s16x4 l0 = tr_read<v_rd_off(D0, 0, 0)>(vb), h0 = tr_read<v_rd_off(D0, 0, 1)>(vb), l1 = tr_read<v_rd_off(D0, 1, 0)>(vb), h1 = tr_read<v_rd_off(D0, 1, 1)>(vb);
;   const s16x4 l2 = tr_read<v_rd_off(D0, 2, 0)>(vb), h2 = tr_read<v_rd_off(D0, 2, 1)>(vb), l3 = tr_read<v_rd_off(D0, 3, 0)>(vb), h3 = tr_read<v_rd_off(D0, 3, 1)>(vb);
;   asm volatile("s_waitcnt lgkmcnt(0)" ::: "memory"); SBAR();
;     ...
;   od = __builtin_amdgcn_mfma_f32_32x32x16_bf16(pa0, PK(l0, h0), od, 0, 0, 0);
;   od = __builtin_amdgcn_mfma_f32_32x32x16_bf16(pa1, PK(l1, h1), od, 0, 0, 0);
;   od = __builtin_amdgcn_mfma_f32_32x32x16_bf16(pa2, PK(l2, h2), od, 0, 0, 0);
;   od = __builtin_amdgcn_mfma_f32_32x32x16_bf16(pa3, PK(l3, h3), od, 0, 0, 0);
;     ...
; }
; __device__ __forceinline__ void pv_d0(f32x16* o, int vb, bf16x8 pa0, bf16x8 pa1, bf16x8 pa2, bf16x8 pa3) {
; __device__ __forceinline__ void qkt_c(f32x16& p0, f32x16& p1, const char* Ks, const bf16x8* qr, const f32x16& negm, int r32, int hi) {
; #pragma unroll
;   for (int d0 = 0; d0 < 4; ++d0) { const int cb = (d0 * 16 + hi * 8) * 2;
;     bf16x8 b0 = *reinterpret_cast<const bf16x8*>(Ks + KSWZ(r32, cb));
;     bf16x8 b1 = *reinterpret_cast<const bf16x8*>(Ks + KSWZ(32 + r32, cb));
;     if (d0 == 0) { p0 = __builtin_amdgcn_mfma_f32_32x32x16_bf16(b0, qr[0], negm, 0, 0, 0); p1 = __builtin_amdgcn_mfma_f32_32x32x16_bf16(b1, qr[0], negm, 0, 0, 0); }
;     else { p0 = __builtin_amdgcn_mfma_f32_32x32x16_bf16(b0, qr[d0], p0, 0, 0, 0); p1 = __builtin_amdgcn_mfma_f32_32x32x16_bf16(b1, qr[d0], p1, 0, 0, 0); } }
; }
; template <int R> __device__ __forceinline__ void bias_r(f32x16& p0, f32x16& p1, float dq, float nslope) {
;   constexpr int C0 = (R & 3) + 8 * (R >> 2);
;   float x0, x1, a0 = p0[R], a1 = p1[R];
;   asm("v_sub_f32_e32 %0, %1, %2" : "=v"(x0) : "n"(__builtin_bit_cast(int, (float)C0)), "v"(dq));
;   asm("v_sub_f32_e32 %0, %1, %2" : "=v"(x1) : "n"(__builtin_bit_cast(int, (float)(C0 + 32))), "v"(dq));
;   asm("v_fma_f32 %0, %1, |%2|, %0" : "+v"(a0) : "v"(nslope), "v"(x0));
;   asm("v_fma_f32 %0, %1, |%2|, %0" : "+v"(a1) : "v"(nslope), "v"(x1));
;   p0[R] = a0; p1[R] = a1;
;   if constexpr (R < 15) bias_r<R + 1>(p0, p1, dq, nslope);
; }
.LBB0_379:
	s_waitcnt lgkmcnt(0)
	s_barrier
	ds_read_b128 v[114:117], v195 offset:49152
	ds_read_b128 v[212:215], v196 offset:49152
	ds_read_b128 v[216:219], v197 offset:49152
	s_andn2_b64 vcc, exec, s[14:15]
	s_add_i32 s46, s47, -1
	s_add_i32 s72, s72, 1
	s_add_i32 s14, s39, -1
	s_cmp_lt_i32 s46, s23
	s_cselect_b32 s14, s72, s14
	s_lshl_b32 s74, s14, 1
	s_sub_i32 s74, s74, s99
	s_add_i32 s75, s74, 1
	s_lshl_b32 s14, s14, 6
	v_cvt_f32_i32_e32 v0, s14
	v_sub_f32_e32 v0, v192, v0
	s_cmp_lt_u32 s75, 2
	s_cbranch_scc1 .Lbc_mix_1
	s_and_b32 s75, s74, 0x80000000
	v_xor_b32_e32 v14, s75, v81
	v_fma_f32 v15, -v14, v0, v82
	v_fmamk_f32 v240, v14, 0x00000000, v15
	v_fmamk_f32 v241, v14, 0x3f800000, v15
	v_fmamk_f32 v242, v14, 0x40000000, v15
	v_fmamk_f32 v243, v14, 0x40400000, v15
	v_fmamk_f32 v244, v14, 0x41000000, v15
	v_fmamk_f32 v245, v14, 0x41100000, v15
	v_fmamk_f32 v246, v14, 0x41200000, v15
	v_fmamk_f32 v247, v14, 0x41300000, v15
	v_fmamk_f32 v248, v14, 0x41800000, v15
	v_fmamk_f32 v249, v14, 0x41880000, v15
	v_fmamk_f32 v250, v14, 0x41900000, v15
	v_fmamk_f32 v251, v14, 0x41980000, v15
	v_fmamk_f32 v252, v14, 0x41c00000, v15
	v_fmamk_f32 v253, v14, 0x41c80000, v15
	v_fmamk_f32 v254, v14, 0x41d00000, v15
	v_fmamk_f32 v255, v14, 0x41d80000, v15
	s_nop 0
	s_waitcnt lgkmcnt(2)
	v_mfma_f32_32x32x16_bf16 v[98:113], v[114:117], v[130:133], v[240:255]
	ds_read_b128 v[220:223], v198 offset:49152
	s_waitcnt lgkmcnt(2)
	v_mfma_f32_32x32x16_bf16 v[98:113], v[212:215], v[134:137], v[98:113]
	ds_read_b128 v[212:215], v195 offset:57344
	s_waitcnt lgkmcnt(2)
	v_mfma_f32_32x32x16_bf16 v[98:113], v[216:219], v[138:141], v[98:113]
	ds_read_b128 v[216:219], v196 offset:57344
	v_fmamk_f32 v240, v14, 0x42000000, v15
	v_fmamk_f32 v241, v14, 0x42040000, v15
	v_fmamk_f32 v242, v14, 0x42080000, v15
	v_fmamk_f32 v243, v14, 0x420c0000, v15
	v_fmamk_f32 v244, v14, 0x42200000, v15
	v_fmamk_f32 v245, v14, 0x42240000, v15
	v_fmamk_f32 v246, v14, 0x42280000, v15
	v_fmamk_f32 v247, v14, 0x422c0000, v15
	s_waitcnt lgkmcnt(2)
	v_mfma_f32_32x32x16_bf16 v[98:113], v[220:223], v[142:145], v[98:113]
	v_fmamk_f32 v248, v14, 0x42400000, v15
	v_fmamk_f32 v249, v14, 0x42440000, v15
	v_fmamk_f32 v250, v14, 0x42480000, v15
	v_fmamk_f32 v251, v14, 0x424c0000, v15
	v_fmamk_f32 v252, v14, 0x42600000, v15
	v_fmamk_f32 v253, v14, 0x42640000, v15
	v_fmamk_f32 v254, v14, 0x42680000, v15
	v_fmamk_f32 v255, v14, 0x426c0000, v15
	ds_read_b128 v[220:223], v197 offset:57344
	s_waitcnt lgkmcnt(2)
	v_mfma_f32_32x32x16_bf16 v[114:129], v[212:215], v[130:133], v[240:255]
	ds_read_b128 v[212:215], v198 offset:57344
	s_waitcnt lgkmcnt(2)
	v_mfma_f32_32x32x16_bf16 v[114:129], v[216:219], v[134:137], v[114:129]
	s_cbranch_vccnz .Lbc_tail_u_1
	ds_read_b64_tr_b16 v[204:205], v193 offset:0
	ds_read_b64_tr_b16 v[206:207], v193 offset:0x800
	ds_read_b64_tr_b16 v[208:209], v193 offset:0x1000
	ds_read_b64_tr_b16 v[210:211], v193 offset:0x1800
	s_waitcnt lgkmcnt(5)
	v_mfma_f32_32x32x16_bf16 v[114:129], v[220:223], v[138:141], v[114:129]
	s_waitcnt lgkmcnt(4)
	v_mfma_f32_32x32x16_bf16 v[114:129], v[212:215], v[142:145], v[114:129]
	ds_read_b64_tr_b16 v[212:213], v193 offset:0x2000
	ds_read_b64_tr_b16 v[214:215], v193 offset:0x2800
	ds_read_b64_tr_b16 v[216:217], v193 offset:0x3000
	ds_read_b64_tr_b16 v[218:219], v193 offset:0x3800
	s_waitcnt lgkmcnt(6)
	v_mfma_f32_32x32x16_bf16 v[64:79], v[2:5], v[204:207], v[64:79]
	ds_read_b64_tr_b16 v[204:205], v193 offset:0x200
	ds_read_b64_tr_b16 v[206:207], v193 offset:0xa00
	s_waitcnt lgkmcnt(6)
	v_mfma_f32_32x32x16_bf16 v[64:79], v[6:9], v[208:211], v[64:79]
	ds_read_b64_tr_b16 v[208:209], v193 offset:0x1200
	ds_read_b64_tr_b16 v[210:211], v193 offset:0x1a00
	s_waitcnt lgkmcnt(6)
	v_mfma_f32_32x32x16_bf16 v[64:79], v[10:13], v[212:215], v[64:79]
	ds_read_b64_tr_b16 v[212:213], v193 offset:0x2200
	ds_read_b64_tr_b16 v[214:215], v193 offset:0x2a00
	ds_read_b64_tr_b16 v[220:221], v193 offset:0x3200
	ds_read_b64_tr_b16 v[222:223], v193 offset:0x3a00
	s_waitcnt lgkmcnt(8)
	v_mfma_f32_32x32x16_bf16 v[64:79], v[162:165], v[216:219], v[64:79]
	s_waitcnt lgkmcnt(6)
	v_mfma_f32_32x32x16_bf16 v[48:63], v[2:5], v[204:207], v[48:63]
	ds_read_b64_tr_b16 v[204:205], v193 offset:0x400
	ds_read_b64_tr_b16 v[206:207], v193 offset:0xc00
	s_waitcnt lgkmcnt(6)
	v_mfma_f32_32x32x16_bf16 v[48:63], v[6:9], v[208:211], v[48:63]
	ds_read_b64_tr_b16 v[208:209], v193 offset:0x1400
	ds_read_b64_tr_b16 v[210:211], v193 offset:0x1c00
	s_waitcnt lgkmcnt(6)
	v_mfma_f32_32x32x16_bf16 v[48:63], v[10:13], v[212:215], v[48:63]
	ds_read_b64_tr_b16 v[212:213], v193 offset:0x2400
	ds_read_b64_tr_b16 v[214:215], v193 offset:0x2c00
	ds_read_b64_tr_b16 v[216:217], v193 offset:0x3400
	ds_read_b64_tr_b16 v[218:219], v193 offset:0x3c00
	s_waitcnt lgkmcnt(8)
	v_mfma_f32_32x32x16_bf16 v[48:63], v[162:165], v[220:223], v[48:63]
	s_waitcnt lgkmcnt(6)
	v_mfma_f32_32x32x16_bf16 v[32:47], v[2:5], v[204:207], v[32:47]
	ds_read_b64_tr_b16 v[204:205], v193 offset:0x600
	ds_read_b64_tr_b16 v[206:207], v193 offset:0xe00
	s_waitcnt lgkmcnt(6)
	v_mfma_f32_32x32x16_bf16 v[32:47], v[6:9], v[208:211], v[32:47]
	ds_read_b64_tr_b16 v[208:209], v193 offset:0x1600
	ds_read_b64_tr_b16 v[210:211], v193 offset:0x1e00
	s_waitcnt lgkmcnt(6)
	v_mfma_f32_32x32x16_bf16 v[32:47], v[10:13], v[212:215], v[32:47]
	ds_read_b64_tr_b16 v[212:213], v193 offset:0x2600
	ds_read_b64_tr_b16 v[214:215], v193 offset:0x2e00
	ds_read_b64_tr_b16 v[220:221], v193 offset:0x3600
	ds_read_b64_tr_b16 v[222:223], v193 offset:0x3e00
	s_waitcnt lgkmcnt(8)
	v_mfma_f32_32x32x16_bf16 v[32:47], v[162:165], v[216:219], v[32:47]
	s_waitcnt lgkmcnt(6)
	v_mfma_f32_32x32x16_bf16 v[16:31], v[2:5], v[204:207], v[16:31]
	s_waitcnt lgkmcnt(4)
	v_mfma_f32_32x32x16_bf16 v[16:31], v[6:9], v[208:211], v[16:31]
	s_waitcnt lgkmcnt(2)
	v_mfma_f32_32x32x16_bf16 v[16:31], v[10:13], v[212:215], v[16:31]
	s_waitcnt lgkmcnt(0)
	v_mfma_f32_32x32x16_bf16 v[16:31], v[162:165], v[220:223], v[16:31]
	s_barrier
	s_branch .Lafter_bias_1

; #define SBAR() __builtin_amdgcn_sched_barrier(0)
; template <int D0> __device__ __forceinline__ void pv_one(f32x16& od, int vb, bf16x8 pa0, bf16x8 pa1, bf16x8 pa2, bf16x8 pa3) {
;   const s16x4 l0 = tr_read<v_rd_off(D0, 0, 0)>(vb), h0 = tr_read<v_rd_off(D0, 0, 1)>(vb), l1 = tr_read<v_rd_off(D0, 1, 0)>(vb), h1 = tr_read<v_rd_off(D0, 1, 1)>(vb);
;   const s16x4 l2 = tr_read<v_rd_off(D0, 2, 0)>(vb), h2 = tr_read<v_rd_off(D0, 2, 1)>(vb), l3 = tr_read<v_rd_off(D0, 3, 0)>(vb), h3 = tr_read<v_rd_off(D0, 3, 1)>(vb);
;   asm volatile("s_waitcnt lgkmcnt(0)" ::: "memory"); SBAR();
;     ...
;   od = __builtin_amdgcn_mfma_f32_32x32x16_bf16(pa0, PK(l0, h0), od, 0, 0, 0);
;   od = __builtin_amdgcn_mfma_f32_32x32x16_bf16(pa1, PK(l1, h1), od, 0, 0, 0);
;   od = __builtin_amdgcn_mfma_f32_32x32x16_bf16(pa2, PK(l2, h2), od, 0, 0, 0);
;   od = __builtin_amdgcn_mfma_f32_32x32x16_bf16(pa3, PK(l3, h3), od, 0, 0, 0);
;     ...
; }
; __device__ __forceinline__ void pv_d0(f32x16* o, int vb, bf16x8 pa0, bf16x8 pa1, bf16x8 pa2, bf16x8 pa3) {
;   pv_one<0>(o[0], vb, pa0, pa1, pa2, pa3); pv_one<1>(o[1], vb, pa0, pa1, pa2, pa3); pv_one<2>(o[2], vb, pa0, pa1, pa2, pa3); pv_one<3>(o[3], vb, pa0, pa1, pa2, pa3);
; }
; __device__ __forceinline__ void attn_unit_pp(int b, int h, int qb, int par, const bf16_t* __restrict__ QBp, const bf16_t* __restrict__ KBp, const bf16_t* __restrict__ VBp, ...
;     ...
;   if (live) pv_d0(o, vb0 + (int)SHM_V, pa0, pa1, pa2, pa3);
.LBB0_409:
	s_cmp_lg_u32 0, -1
	s_cselect_b32 s2, 0, 0
	s_addk_i32 s2, 0x4000
	v_add_u32_e32 v0, s2, v191
	ds_read_b64_tr_b16 v[82:83], v0 offset:0
	ds_read_b64_tr_b16 v[84:85], v0 offset:0x800
	ds_read_b64_tr_b16 v[86:87], v0 offset:0x1000
	ds_read_b64_tr_b16 v[88:89], v0 offset:0x1800
	ds_read_b64_tr_b16 v[90:91], v0 offset:0x2000
	ds_read_b64_tr_b16 v[92:93], v0 offset:0x2800
	ds_read_b64_tr_b16 v[94:95], v0 offset:0x3000
	ds_read_b64_tr_b16 v[96:97], v0 offset:0x3800
	s_waitcnt lgkmcnt(6)
	v_mfma_f32_32x32x16_bf16 v[64:79], v[2:5], v[82:85], v[64:79]
	ds_read_b64_tr_b16 v[82:83], v0 offset:0x200
	ds_read_b64_tr_b16 v[84:85], v0 offset:0xa00
	s_waitcnt lgkmcnt(6)
	v_mfma_f32_32x32x16_bf16 v[64:79], v[6:9], v[86:89], v[64:79]
	ds_read_b64_tr_b16 v[86:87], v0 offset:0x1200
	ds_read_b64_tr_b16 v[88:89], v0 offset:0x1a00
	s_waitcnt lgkmcnt(6)
	v_mfma_f32_32x32x16_bf16 v[64:79], v[10:13], v[90:93], v[64:79]
	ds_read_b64_tr_b16 v[90:91], v0 offset:0x2200
	ds_read_b64_tr_b16 v[92:93], v0 offset:0x2a00
	ds_read_b64_tr_b16 v[98:99], v0 offset:0x3200
	ds_read_b64_tr_b16 v[100:101], v0 offset:0x3a00
	s_waitcnt lgkmcnt(8)
	v_mfma_f32_32x32x16_bf16 v[64:79], v[162:165], v[94:97], v[64:79]
	s_waitcnt lgkmcnt(6)
	v_mfma_f32_32x32x16_bf16 v[48:63], v[2:5], v[82:85], v[48:63]
	ds_read_b64_tr_b16 v[82:83], v0 offset:0x400
	ds_read_b64_tr_b16 v[84:85], v0 offset:0xc00
	s_waitcnt lgkmcnt(6)
	v_mfma_f32_32x32x16_bf16 v[48:63], v[6:9], v[86:89], v[48:63]
	ds_read_b64_tr_b16 v[86:87], v0 offset:0x1400
	ds_read_b64_tr_b16 v[88:89], v0 offset:0x1c00
	s_waitcnt lgkmcnt(6)
	v_mfma_f32_32x32x16_bf16 v[48:63], v[10:13], v[90:93], v[48:63]
	ds_read_b64_tr_b16 v[90:91], v0 offset:0x2400
	ds_read_b64_tr_b16 v[92:93], v0 offset:0x2c00
	ds_read_b64_tr_b16 v[94:95], v0 offset:0x3400
	ds_read_b64_tr_b16 v[96:97], v0 offset:0x3c00
	s_waitcnt lgkmcnt(8)
	v_mfma_f32_32x32x16_bf16 v[48:63], v[162:165], v[98:101], v[48:63]
	s_waitcnt lgkmcnt(6)
	v_mfma_f32_32x32x16_bf16 v[32:47], v[2:5], v[82:85], v[32:47]
	ds_read_b64_tr_b16 v[82:83], v0 offset:0x600
	ds_read_b64_tr_b16 v[84:85], v0 offset:0xe00
	s_waitcnt lgkmcnt(6)
	v_mfma_f32_32x32x16_bf16 v[32:47], v[6:9], v[86:89], v[32:47]
	ds_read_b64_tr_b16 v[86:87], v0 offset:0x1600
	ds_read_b64_tr_b16 v[88:89], v0 offset:0x1e00
	s_waitcnt lgkmcnt(6)
	v_mfma_f32_32x32x16_bf16 v[32:47], v[10:13], v[90:93], v[32:47]
	ds_read_b64_tr_b16 v[90:91], v0 offset:0x2600
	ds_read_b64_tr_b16 v[92:93], v0 offset:0x2e00
	ds_read_b64_tr_b16 v[98:99], v0 offset:0x3600
	ds_read_b64_tr_b16 v[100:101], v0 offset:0x3e00
	s_waitcnt lgkmcnt(8)
	v_mfma_f32_32x32x16_bf16 v[32:47], v[162:165], v[94:97], v[32:47]
	s_waitcnt lgkmcnt(6)
	v_mfma_f32_32x32x16_bf16 v[16:31], v[2:5], v[82:85], v[16:31]
	s_waitcnt lgkmcnt(4)
	v_mfma_f32_32x32x16_bf16 v[16:31], v[6:9], v[86:89], v[16:31]
	s_waitcnt lgkmcnt(2)
	v_mfma_f32_32x32x16_bf16 v[16:31], v[10:13], v[90:93], v[16:31]
	s_waitcnt lgkmcnt(0)
	v_mfma_f32_32x32x16_bf16 v[16:31], v[162:165], v[98:101], v[16:31]
	s_andn2_b64 vcc, exec, s[12:13]
	s_cbranch_vccnz .LBB0_405
